# v6 + XCD leader L1 invalidate issued with the L2 writeback, no drain before local release
# speedup vs baseline: 1.0081x; 1.0081x over previous
.LBB0_181:
	s_andn2_saveexec_b64 s[0:1], s[2:3]
	s_cbranch_execz .LBB0_197
	v_mov_b32_e32 v1, s38
	v_add_co_u32_e32 v4, vcc, 0x3000, v1
	v_mov_b32_e32 v1, s39
	buffer_wbl2 sc1
	buffer_inv sc1
	s_waitcnt vmcnt(0)
	v_addc_co_u32_e32 v5, vcc, 0, v1, vcc
	v_mov_b32_e32 v1, 1
	flat_atomic_add v1, v[4:5], v1 offset:1024 sc0
	v_cvt_f32_u32_e32 v3, v2
	v_sub_u32_e32 v4, 0, v2
	s_add_u32 s2, s38, 0x3500
	s_addc_u32 s3, s39, 0
	v_rcp_iflag_f32_e32 v3, v3
	s_mov_b64 s[6:7], -1
	v_mul_f32_e32 v3, 0x4f7ffffe, v3
	v_cvt_u32_f32_e32 v3, v3
	v_mul_lo_u32 v4, v4, v3
	v_mul_hi_u32 v4, v3, v4
	v_add_u32_e32 v3, v3, v4
	s_waitcnt vmcnt(0) lgkmcnt(0)
	v_mul_hi_u32 v3, v1, v3
	v_mul_lo_u32 v5, v3, v2
	v_add_u32_e32 v4, 1, v1
	v_sub_u32_e32 v1, v1, v5
	v_add_u32_e32 v6, 1, v3
	v_cmp_ge_u32_e32 vcc, v1, v2
	v_sub_u32_e32 v5, v1, v2
	s_nop 0
	v_cndmask_b32_e32 v3, v3, v6, vcc
	v_cndmask_b32_e32 v1, v1, v5, vcc
	v_add_u32_e32 v5, 1, v3
	v_cmp_ge_u32_e32 vcc, v1, v2
	s_nop 1
	v_cndmask_b32_e32 v1, v3, v5, vcc
	v_mad_u64_u32 v[2:3], s[0:1], v2, v1, v[2:3]
	v_cmp_ne_u32_e32 vcc, v4, v2
	v_mov_b64_e32 v[2:3], s[2:3]
	s_and_saveexec_b64 s[4:5], vcc
	s_cbranch_execz .LBB0_194
	v_mov_b64_e32 v[2:3], s[2:3]
	flat_load_dword v2, v[2:3] sc1
	s_mov_b64 s[10:11], 0
	s_waitcnt vmcnt(0) lgkmcnt(0)
	v_cmp_eq_u32_e32 vcc, v2, v1
	s_and_saveexec_b64 s[8:9], vcc
	s_cbranch_execz .LBB0_193
	s_add_u32 s6, s38, 0x200
	s_addc_u32 s7, s39, 0
	s_mov_b32 s0, 1
	s_branch .LBB0_186

.LBB0_196:
	s_or_b64 exec, exec, s[2:3]
	s_add_i32 s0, s13, 0x900
	s_mov_b32 s1, 0
	s_lshl_b64 s[0:1], s[0:1], 2
	s_add_u32 s0, s38, s0
	s_addc_u32 s1, s39, s1
	v_mov_b32_e32 v1, 1
	v_mov_b64_e32 v[2:3], s[0:1]
	flat_atomic_add v[2:3], v1
	s_waitcnt vmcnt(0)

.LBB0_362:
	s_andn2_saveexec_b64 s[2:3], s[2:3]
	s_cbranch_execz .LBB0_378
	v_mov_b32_e32 v1, s38
	v_add_co_u32_e32 v4, vcc, 0x3000, v1
	v_mov_b32_e32 v1, s39
	buffer_wbl2 sc1
	buffer_inv sc1
	s_waitcnt vmcnt(0)
	v_addc_co_u32_e32 v5, vcc, 0, v1, vcc
	v_mov_b32_e32 v1, 1
	flat_atomic_add v1, v[4:5], v1 offset:1024 sc0
	v_cvt_f32_u32_e32 v3, v2
	v_sub_u32_e32 v4, 0, v2
	s_add_u32 s4, s38, 0x3500
	s_addc_u32 s5, s39, 0
	v_rcp_iflag_f32_e32 v3, v3
	s_mov_b64 s[8:9], -1
	v_mul_f32_e32 v3, 0x4f7ffffe, v3
	v_cvt_u32_f32_e32 v3, v3
	v_mul_lo_u32 v4, v4, v3
	v_mul_hi_u32 v4, v3, v4
	v_add_u32_e32 v3, v3, v4
	s_waitcnt vmcnt(0) lgkmcnt(0)
	v_mul_hi_u32 v3, v1, v3
	v_mul_lo_u32 v5, v3, v2
	v_add_u32_e32 v4, 1, v1
	v_sub_u32_e32 v1, v1, v5
	v_add_u32_e32 v6, 1, v3
	v_cmp_ge_u32_e32 vcc, v1, v2
	v_sub_u32_e32 v5, v1, v2
	s_nop 0
	v_cndmask_b32_e32 v3, v3, v6, vcc
	v_cndmask_b32_e32 v1, v1, v5, vcc
	v_add_u32_e32 v5, 1, v3
	v_cmp_ge_u32_e32 vcc, v1, v2
	s_nop 1
	v_cndmask_b32_e32 v1, v3, v5, vcc
	v_mad_u64_u32 v[2:3], s[0:1], v2, v1, v[2:3]
	v_cmp_ne_u32_e32 vcc, v4, v2
	v_mov_b64_e32 v[2:3], s[4:5]
	s_and_saveexec_b64 s[6:7], vcc
	s_cbranch_execz .LBB0_375
	v_mov_b64_e32 v[2:3], s[4:5]
	flat_load_dword v2, v[2:3] sc1
	s_mov_b64 s[14:15], 0
	s_waitcnt vmcnt(0) lgkmcnt(0)
	v_cmp_eq_u32_e32 vcc, v2, v1
	s_and_saveexec_b64 s[10:11], vcc
	s_cbranch_execz .LBB0_374
	s_add_u32 s8, s38, 0x200
	s_addc_u32 s9, s39, 0
	s_mov_b32 s0, 1
	s_branch .LBB0_367

.LBB0_377:
	s_or_b64 exec, exec, s[4:5]
	s_add_i32 s0, s13, 0x900
	s_mov_b32 s1, 0
	s_lshl_b64 s[0:1], s[0:1], 2
	s_add_u32 s0, s38, s0
	s_addc_u32 s1, s39, s1
	v_mov_b32_e32 v1, 1
	v_mov_b64_e32 v[2:3], s[0:1]
	flat_atomic_add v[2:3], v1
	s_waitcnt vmcnt(0)

.LBB0_380:
	s_or_b64 exec, exec, s[4:5]
	s_add_i32 s86, s26, 0x900
	s_lshl_b64 s[0:1], s[86:87], 2
	s_add_u32 s0, s38, s0
	s_addc_u32 s1, s39, s1
	v_mov_b64_e32 v[2:3], s[0:1]
	flat_atomic_add v[2:3], v1
	s_waitcnt vmcnt(0)

.LBB0_557:
	s_andn2_saveexec_b64 s[2:3], s[2:3]
	s_cbranch_execz .LBB0_573
	v_mov_b32_e32 v3, s38
	v_add_co_u32_e32 v4, vcc, 0x3000, v3
	v_mov_b32_e32 v3, s39
	buffer_wbl2 sc1
	buffer_inv sc1
	s_waitcnt vmcnt(0)
	v_addc_co_u32_e32 v5, vcc, 0, v3, vcc
	flat_atomic_add v3, v[4:5], v1 offset:1024 sc0
	v_cvt_f32_u32_e32 v4, v2
	v_sub_u32_e32 v5, 0, v2
	s_add_u32 s4, s38, 0x3500
	s_addc_u32 s5, s39, 0
	v_rcp_iflag_f32_e32 v4, v4
	s_mov_b64 s[8:9], -1
	v_mul_f32_e32 v4, 0x4f7ffffe, v4
	v_cvt_u32_f32_e32 v4, v4
	v_mul_lo_u32 v5, v5, v4
	v_mul_hi_u32 v5, v4, v5
	v_add_u32_e32 v4, v4, v5
	s_waitcnt vmcnt(0) lgkmcnt(0)
	v_mul_hi_u32 v4, v3, v4
	v_mul_lo_u32 v5, v4, v2
	v_sub_u32_e32 v5, v3, v5
	v_cmp_ge_u32_e32 vcc, v5, v2
	v_add_u32_e32 v6, 1, v4
	s_nop 0
	v_cndmask_b32_e32 v4, v4, v6, vcc
	v_sub_u32_e32 v6, v5, v2
	v_cndmask_b32_e32 v5, v5, v6, vcc
	v_cmp_ge_u32_e32 vcc, v5, v2
	v_add_u32_e32 v5, 1, v4
	s_nop 0
	v_cndmask_b32_e32 v4, v4, v5, vcc
	v_add_u32_e32 v5, 1, v3
	v_mad_u64_u32 v[2:3], s[0:1], v2, v4, v[2:3]
	v_cmp_ne_u32_e32 vcc, v5, v2
	v_mov_b64_e32 v[2:3], s[4:5]
	s_and_saveexec_b64 s[6:7], vcc
	s_cbranch_execz .LBB0_570
	v_mov_b64_e32 v[2:3], s[4:5]
	flat_load_dword v2, v[2:3] sc1
	s_mov_b64 s[14:15], 0
	s_waitcnt vmcnt(0) lgkmcnt(0)
	v_cmp_eq_u32_e32 vcc, v2, v4
	s_and_saveexec_b64 s[10:11], vcc
	s_cbranch_execz .LBB0_569
	s_add_u32 s8, s38, 0x200
	s_addc_u32 s9, s39, 0
	s_mov_b32 s0, 1
	s_branch .LBB0_562

.LBB0_607:
	s_andn2_saveexec_b64 s[0:1], s[2:3]
	s_cbranch_execz .LBB0_623
	v_mov_b32_e32 v3, s38
	v_add_co_u32_e32 v4, vcc, 0x3000, v3
	v_mov_b32_e32 v3, s39
	buffer_wbl2 sc1
	buffer_inv sc1
	s_waitcnt vmcnt(0)
	v_addc_co_u32_e32 v5, vcc, 0, v3, vcc
	flat_atomic_add v3, v[4:5], v1 offset:1024 sc0
	v_cvt_f32_u32_e32 v4, v2
	v_sub_u32_e32 v5, 0, v2
	s_add_u32 s2, s38, 0x3500
	s_addc_u32 s3, s39, 0
	v_rcp_iflag_f32_e32 v4, v4
	s_mov_b64 s[6:7], -1
	v_mul_f32_e32 v4, 0x4f7ffffe, v4
	v_cvt_u32_f32_e32 v4, v4
	v_mul_lo_u32 v5, v5, v4
	v_mul_hi_u32 v5, v4, v5
	v_add_u32_e32 v4, v4, v5
	s_waitcnt vmcnt(0) lgkmcnt(0)
	v_mul_hi_u32 v4, v3, v4
	v_mul_lo_u32 v5, v4, v2
	v_sub_u32_e32 v5, v3, v5
	v_cmp_ge_u32_e32 vcc, v5, v2
	v_add_u32_e32 v6, 1, v4
	s_nop 0
	v_cndmask_b32_e32 v4, v4, v6, vcc
	v_sub_u32_e32 v6, v5, v2
	v_cndmask_b32_e32 v5, v5, v6, vcc
	v_cmp_ge_u32_e32 vcc, v5, v2
	v_add_u32_e32 v5, 1, v4
	s_nop 0
	v_cndmask_b32_e32 v4, v4, v5, vcc
	v_add_u32_e32 v5, 1, v3
	v_mad_u64_u32 v[2:3], s[0:1], v2, v4, v[2:3]
	v_cmp_ne_u32_e32 vcc, v5, v2
	v_mov_b64_e32 v[2:3], s[2:3]
	s_and_saveexec_b64 s[4:5], vcc
	s_cbranch_execz .LBB0_620
	v_mov_b64_e32 v[2:3], s[2:3]
	flat_load_dword v2, v[2:3] sc1
	s_mov_b64 s[10:11], 0
	s_waitcnt vmcnt(0) lgkmcnt(0)
	v_cmp_eq_u32_e32 vcc, v2, v4
	s_and_saveexec_b64 s[8:9], vcc
	s_cbranch_execz .LBB0_619
	s_add_u32 s6, s38, 0x200
	s_addc_u32 s7, s39, 0
	s_mov_b32 s0, 1
	s_branch .LBB0_612

.LBB0_622:
	s_or_b64 exec, exec, s[2:3]
	s_add_i32 s86, s24, 0x900
	s_lshl_b64 s[0:1], s[86:87], 2
	s_add_u32 s0, s38, s0
	s_addc_u32 s1, s39, s1
	v_mov_b64_e32 v[2:3], s[0:1]
	flat_atomic_add v[2:3], v1
	s_waitcnt vmcnt(0)

.LBB0_936:
	s_andn2_saveexec_b64 s[4:5], s[4:5]
	s_cbranch_execz .LBB0_952
	v_mov_b32_e32 v3, s2
	v_add_co_u32_e32 v4, vcc, 0x3000, v3
	v_mov_b32_e32 v3, s3
	buffer_wbl2 sc1
	buffer_inv sc1
	s_waitcnt vmcnt(0)
	v_addc_co_u32_e32 v5, vcc, 0, v3, vcc
	flat_atomic_add v3, v[4:5], v1 offset:1024 sc0
	v_cvt_f32_u32_e32 v4, v2
	v_sub_u32_e32 v5, 0, v2
	s_add_u32 s6, s2, 0x3500
	s_addc_u32 s7, s3, 0
	v_rcp_iflag_f32_e32 v4, v4
	s_mov_b64 s[10:11], -1
	v_mul_f32_e32 v4, 0x4f7ffffe, v4
	v_cvt_u32_f32_e32 v4, v4
	v_mul_lo_u32 v5, v5, v4
	v_mul_hi_u32 v5, v4, v5
	v_add_u32_e32 v4, v4, v5
	s_waitcnt vmcnt(0) lgkmcnt(0)
	v_mul_hi_u32 v4, v3, v4
	v_mul_lo_u32 v5, v4, v2
	v_sub_u32_e32 v5, v3, v5
	v_cmp_ge_u32_e32 vcc, v5, v2
	v_add_u32_e32 v6, 1, v4
	s_nop 0
	v_cndmask_b32_e32 v4, v4, v6, vcc
	v_sub_u32_e32 v6, v5, v2
	v_cndmask_b32_e32 v5, v5, v6, vcc
	v_cmp_ge_u32_e32 vcc, v5, v2
	v_add_u32_e32 v5, 1, v4
	s_nop 0
	v_cndmask_b32_e32 v4, v4, v5, vcc
	v_add_u32_e32 v5, 1, v3
	v_mad_u64_u32 v[2:3], s[0:1], v2, v4, v[2:3]
	v_cmp_ne_u32_e32 vcc, v5, v2
	v_mov_b64_e32 v[2:3], s[6:7]
	s_and_saveexec_b64 s[8:9], vcc
	s_cbranch_execz .LBB0_949
	v_mov_b64_e32 v[2:3], s[6:7]
	flat_load_dword v2, v[2:3] sc1
	s_mov_b64 s[16:17], 0
	s_waitcnt vmcnt(0) lgkmcnt(0)
	v_cmp_eq_u32_e32 vcc, v2, v4
	s_and_saveexec_b64 s[14:15], vcc
	s_cbranch_execz .LBB0_948
	s_add_u32 s10, s2, 0x200
	s_addc_u32 s11, s3, 0
	s_mov_b32 s0, 1
	s_branch .LBB0_941

.LBB0_951:
	s_or_b64 exec, exec, s[6:7]
	s_add_i32 s86, s28, 0x900
	s_lshl_b64 s[0:1], s[86:87], 2
	s_add_u32 s0, s2, s0
	s_addc_u32 s1, s3, s1
	v_mov_b64_e32 v[2:3], s[0:1]
	flat_atomic_add v[2:3], v1
	s_waitcnt vmcnt(0)

.LBB0_1025:
	s_andn2_saveexec_b64 s[6:7], s[6:7]
	s_cbranch_execz .LBB0_1041
	v_mov_b32_e32 v3, s4
	v_add_co_u32_e32 v4, vcc, 0x3000, v3
	v_mov_b32_e32 v3, s5
	buffer_wbl2 sc1
	buffer_inv sc1
	s_waitcnt vmcnt(0)
	v_addc_co_u32_e32 v5, vcc, 0, v3, vcc
	flat_atomic_add v3, v[4:5], v1 offset:1024 sc0
	v_cvt_f32_u32_e32 v4, v2
	v_sub_u32_e32 v5, 0, v2
	s_add_u32 s8, s4, 0x3500
	s_addc_u32 s9, s5, 0
	v_rcp_iflag_f32_e32 v4, v4
	s_mov_b64 s[14:15], -1
	v_mul_f32_e32 v4, 0x4f7ffffe, v4
	v_cvt_u32_f32_e32 v4, v4
	v_mul_lo_u32 v5, v5, v4
	v_mul_hi_u32 v5, v4, v5
	v_add_u32_e32 v4, v4, v5
	s_waitcnt vmcnt(0) lgkmcnt(0)
	v_mul_hi_u32 v4, v3, v4
	v_mul_lo_u32 v5, v4, v2
	v_sub_u32_e32 v5, v3, v5
	v_cmp_ge_u32_e32 vcc, v5, v2
	v_add_u32_e32 v6, 1, v4
	s_nop 0
	v_cndmask_b32_e32 v4, v4, v6, vcc
	v_sub_u32_e32 v6, v5, v2
	v_cndmask_b32_e32 v5, v5, v6, vcc
	v_cmp_ge_u32_e32 vcc, v5, v2
	v_add_u32_e32 v5, 1, v4
	s_nop 0
	v_cndmask_b32_e32 v4, v4, v5, vcc
	v_add_u32_e32 v5, 1, v3
	v_mad_u64_u32 v[2:3], s[0:1], v2, v4, v[2:3]
	v_cmp_ne_u32_e32 vcc, v5, v2
	v_mov_b64_e32 v[2:3], s[8:9]
	s_and_saveexec_b64 s[10:11], vcc
	s_cbranch_execz .LBB0_1038
	v_mov_b64_e32 v[2:3], s[8:9]
	flat_load_dword v2, v[2:3] sc1
	s_mov_b64 s[18:19], 0
	s_waitcnt vmcnt(0) lgkmcnt(0)
	v_cmp_eq_u32_e32 vcc, v2, v4
	s_and_saveexec_b64 s[16:17], vcc
	s_cbranch_execz .LBB0_1037
	s_add_u32 s14, s4, 0x200
	s_addc_u32 s15, s5, 0
	s_mov_b32 s0, 1
	s_branch .LBB0_1030

.LBB0_1040:
	s_or_b64 exec, exec, s[8:9]
	s_add_i32 s86, s30, 0x900
	s_lshl_b64 s[0:1], s[86:87], 2
	s_add_u32 s0, s4, s0
	s_addc_u32 s1, s5, s1
	v_mov_b64_e32 v[2:3], s[0:1]
	flat_atomic_add v[2:3], v1
	s_waitcnt vmcnt(0)

.LBB0_1281:
	s_andn2_saveexec_b64 s[8:9], s[8:9]
	s_cbranch_execz .LBB0_1297
	v_mov_b32_e32 v3, s4
	v_add_co_u32_e32 v4, vcc, 0x3000, v3
	v_mov_b32_e32 v3, s5
	buffer_wbl2 sc1
	buffer_inv sc1
	s_waitcnt vmcnt(0)
	v_addc_co_u32_e32 v5, vcc, 0, v3, vcc
	flat_atomic_add v3, v[4:5], v1 offset:1024 sc0
	v_cvt_f32_u32_e32 v4, v2
	v_sub_u32_e32 v5, 0, v2
	s_add_u32 s10, s4, 0x3500
	s_addc_u32 s11, s5, 0
	v_rcp_iflag_f32_e32 v4, v4
	s_mov_b64 s[16:17], -1
	v_mul_f32_e32 v4, 0x4f7ffffe, v4
	v_cvt_u32_f32_e32 v4, v4
	v_mul_lo_u32 v5, v5, v4
	v_mul_hi_u32 v5, v4, v5
	v_add_u32_e32 v4, v4, v5
	s_waitcnt vmcnt(0) lgkmcnt(0)
	v_mul_hi_u32 v4, v3, v4
	v_mul_lo_u32 v5, v4, v2
	v_sub_u32_e32 v5, v3, v5
	v_cmp_ge_u32_e32 vcc, v5, v2
	v_add_u32_e32 v6, 1, v4
	s_nop 0
	v_cndmask_b32_e32 v4, v4, v6, vcc
	v_sub_u32_e32 v6, v5, v2
	v_cndmask_b32_e32 v5, v5, v6, vcc
	v_cmp_ge_u32_e32 vcc, v5, v2
	v_add_u32_e32 v5, 1, v4
	s_nop 0
	v_cndmask_b32_e32 v4, v4, v5, vcc
	v_add_u32_e32 v5, 1, v3
	v_mad_u64_u32 v[2:3], s[0:1], v2, v4, v[2:3]
	v_cmp_ne_u32_e32 vcc, v5, v2
	v_mov_b64_e32 v[2:3], s[10:11]
	s_and_saveexec_b64 s[14:15], vcc
	s_cbranch_execz .LBB0_1294
	v_mov_b64_e32 v[2:3], s[10:11]
	flat_load_dword v2, v[2:3] sc1
	s_mov_b64 s[20:21], 0
	s_waitcnt vmcnt(0) lgkmcnt(0)
	v_cmp_eq_u32_e32 vcc, v2, v4
	s_and_saveexec_b64 s[18:19], vcc
	s_cbranch_execz .LBB0_1293
	s_add_u32 s16, s4, 0x200
	s_addc_u32 s17, s5, 0
	s_mov_b32 s0, 1
	s_branch .LBB0_1286

.LBB0_1296:
	s_or_b64 exec, exec, s[10:11]
	s_add_i32 s86, s34, 0x900
	s_lshl_b64 s[0:1], s[86:87], 2
	s_add_u32 s0, s4, s0
	s_addc_u32 s1, s5, s1
	v_mov_b64_e32 v[2:3], s[0:1]
	flat_atomic_add v[2:3], v1
	s_waitcnt vmcnt(0)

.LBB0_1684:
	s_andn2_saveexec_b64 s[2:3], s[2:3]
	s_cbranch_execz .LBB0_1700
	v_mov_b32_e32 v3, s4
	v_add_co_u32_e32 v4, vcc, 0x3000, v3
	v_mov_b32_e32 v3, s5
	buffer_wbl2 sc1
	buffer_inv sc1
	s_waitcnt vmcnt(0)
	v_addc_co_u32_e32 v5, vcc, 0, v3, vcc
	flat_atomic_add v3, v[4:5], v1 offset:1024 sc0
	v_cvt_f32_u32_e32 v4, v2
	v_sub_u32_e32 v5, 0, v2
	s_add_u32 s8, s4, 0x3500
	s_addc_u32 s9, s5, 0
	v_rcp_iflag_f32_e32 v4, v4
	s_mov_b64 s[14:15], -1
	v_mul_f32_e32 v4, 0x4f7ffffe, v4
	v_cvt_u32_f32_e32 v4, v4
	v_mul_lo_u32 v5, v5, v4
	v_mul_hi_u32 v5, v4, v5
	v_add_u32_e32 v4, v4, v5
	s_waitcnt vmcnt(0) lgkmcnt(0)
	v_mul_hi_u32 v4, v3, v4
	v_mul_lo_u32 v5, v4, v2
	v_sub_u32_e32 v5, v3, v5
	v_cmp_ge_u32_e32 vcc, v5, v2
	v_add_u32_e32 v6, 1, v4
	s_nop 0
	v_cndmask_b32_e32 v4, v4, v6, vcc
	v_sub_u32_e32 v6, v5, v2
	v_cndmask_b32_e32 v5, v5, v6, vcc
	v_cmp_ge_u32_e32 vcc, v5, v2
	v_add_u32_e32 v5, 1, v4
	s_nop 0
	v_cndmask_b32_e32 v4, v4, v5, vcc
	v_add_u32_e32 v5, 1, v3
	v_mad_u64_u32 v[2:3], s[0:1], v2, v4, v[2:3]
	v_cmp_ne_u32_e32 vcc, v5, v2
	v_mov_b64_e32 v[2:3], s[8:9]
	s_and_saveexec_b64 s[10:11], vcc
	s_cbranch_execz .LBB0_1697
	v_mov_b64_e32 v[2:3], s[8:9]
	flat_load_dword v2, v[2:3] sc1
	s_mov_b64 s[18:19], 0
	s_waitcnt vmcnt(0) lgkmcnt(0)
	v_cmp_eq_u32_e32 vcc, v2, v4
	s_and_saveexec_b64 s[16:17], vcc
	s_cbranch_execz .LBB0_1696
	s_add_u32 s14, s4, 0x200
	s_addc_u32 s15, s5, 0
	s_mov_b32 s0, 1
	s_branch .LBB0_1689

.LBB0_1847:
	v_mov_b32_e32 v3, s38
	v_add_co_u32_e32 v4, vcc, 0x3000, v3
	v_mov_b32_e32 v3, s39
	buffer_wbl2 sc1
	buffer_inv sc1
	s_waitcnt vmcnt(0)
	v_addc_co_u32_e32 v5, vcc, 0, v3, vcc
	flat_atomic_add v3, v[4:5], v1 offset:1024 sc0
	v_cvt_f32_u32_e32 v4, v2
	v_sub_u32_e32 v5, 0, v2
	s_add_u32 s4, s38, 0x3500
	s_addc_u32 s5, s39, 0
	v_rcp_iflag_f32_e32 v4, v4
	s_mov_b64 s[8:9], -1
	v_mul_f32_e32 v4, 0x4f7ffffe, v4
	v_cvt_u32_f32_e32 v4, v4
	v_mul_lo_u32 v5, v5, v4
	v_mul_hi_u32 v5, v4, v5
	v_add_u32_e32 v4, v4, v5
	s_waitcnt vmcnt(0) lgkmcnt(0)
	v_mul_hi_u32 v4, v3, v4
	v_mul_lo_u32 v5, v4, v2
	v_sub_u32_e32 v5, v3, v5
	v_cmp_ge_u32_e32 vcc, v5, v2
	v_add_u32_e32 v6, 1, v4
	s_nop 0
	v_cndmask_b32_e32 v4, v4, v6, vcc
	v_sub_u32_e32 v6, v5, v2
	v_cndmask_b32_e32 v5, v5, v6, vcc
	v_cmp_ge_u32_e32 vcc, v5, v2
	v_add_u32_e32 v5, 1, v4
	s_nop 0
	v_cndmask_b32_e32 v4, v4, v5, vcc
	v_add_u32_e32 v5, 1, v3
	v_mad_u64_u32 v[2:3], s[0:1], v2, v4, v[2:3]
	v_cmp_ne_u32_e32 vcc, v5, v2
	v_mov_b64_e32 v[2:3], s[4:5]
	s_and_saveexec_b64 s[6:7], vcc
	s_cbranch_execz .LBB0_1859
	v_mov_b64_e32 v[2:3], s[4:5]
	flat_load_dword v2, v[2:3] sc1
	s_mov_b64 s[14:15], 0
	s_waitcnt vmcnt(0) lgkmcnt(0)
	v_cmp_eq_u32_e32 vcc, v2, v4
	s_and_saveexec_b64 s[10:11], vcc
	s_cbranch_execz .LBB0_1858
	s_add_u32 s8, s38, 0x200
	s_addc_u32 s9, s39, 0
	s_mov_b32 s0, 1
	s_branch .LBB0_1851
